# phase 2: stage Z rows prefetched into 7 staging quads, mu table in LDS (on v30)
# baseline (speedup 1.0000x reference)
.LBB0_281:
	s_cmp_lt_i32 s92, 3
	s_cselect_b64 s[0:1], -1, 0
	s_cmp_gt_i32 s93, 2
	s_cselect_b64 s[4:5], -1, 0
	s_and_b64 s[0:1], s[0:1], s[4:5]
	s_andn2_b64 vcc, exec, s[0:1]
	s_cbranch_vccnz .LBB0_359
	v_readlane_b32 s0, v254, 0
	s_cmpk_gt_i32 s0, 0xff
	v_readfirstlane_b32 s0, v0
	v_readlane_b32 s1, v254, 1
	s_cbranch_scc1 .LBB0_305
	s_add_u32 s34, s66, 0x25f00000
	s_addc_u32 s35, s67, 0
	s_add_u32 s36, s66, 0x3cca0000
	s_addc_u32 s37, s67, 0
	v_lshrrev_b32_e32 v2, 1, v0
	s_add_u32 s38, s66, 0x44cc0000
	v_readlane_b32 s4, v254, 4
	v_and_b32_e32 v14, 24, v2
	s_addc_u32 s39, s67, 0
	v_readlane_b32 s5, v254, 5
	v_lshlrev_b32_e32 v150, 1, v14
	v_mov_b32_e32 v151, 0
	s_mov_b32 s1, 0x4924925
	s_add_u32 s40, s66, 0x48cd0000
	v_lshl_add_u64 v[2:3], s[66:67], 0, v[150:151]
	s_mov_b64 s[4:5], 0x556a0000
	v_mul_hi_u32 v204, v0, s1
	s_addc_u32 s41, s67, 0
	v_readlane_b32 s12, v254, 12
	v_lshl_add_u64 v[152:153], v[2:3], 0, s[4:5]
	v_mul_u32_u24_e32 v2, 56, v204
	v_or_b32_e32 v5, 0x200, v0
	v_readlane_b32 s13, v254, 13
	s_add_u32 s28, s12, 0x6000
	v_sub_u32_e32 v4, v0, v2
	v_mul_hi_u32 v205, v5, s1
	v_readlane_b32 s6, v254, 6
	v_readlane_b32 s7, v254, 7
	s_addc_u32 s29, s13, 0
	s_sub_u32 s94, 0xe400, s28
	v_lshlrev_b32_e32 v224, 4, v0
	s_movk_i32 s95, 0x70
	v_cmp_gt_u32_e64 s[96:97], s95, v0
	v_add_u32_e32 v225, 0xe400, v224
	s_nop 3
	s_and_saveexec_b64 s[96:97], s[96:97]
	global_load_dwordx4 v[228:231], v224, s[28:29]
	s_waitcnt vmcnt(0)
	ds_write_b128 v225, v[228:231]
	s_waitcnt lgkmcnt(0)
	s_or_b64 exec, exec, s[96:97]
	v_lshlrev_b32_e32 v2, 3, v4
	v_mov_b32_e32 v3, v151
	v_mul_u32_u24_e32 v6, 56, v205
	v_sub_u32_e32 v5, v5, v6
	v_lshl_add_u64 v[154:155], v[2:3], 2, s[28:29]
	v_cmp_gt_u32_e64 s[4:5], 12, v4
	v_cmp_gt_u32_e64 s[6:7], 24, v4
	v_mul_u32_u24_e32 v3, 0x390, v204
	v_lshlrev_b32_e32 v4, 4, v4
	v_add3_u32 v206, 0, v3, v4
	v_mul_u32_u24_e32 v3, 0x390, v205
	v_lshlrev_b32_e32 v4, 4, v5
	v_add3_u32 v207, 0, v3, v4
	v_or_b32_e32 v3, 0x400, v0
	v_mul_hi_u32 v208, v3, s1
	v_mul_u32_u24_e32 v4, 56, v208
	v_or_b32_e32 v6, 0x600, v0
	v_readlane_b32 s8, v254, 8
	v_readlane_b32 s9, v254, 9
	v_readlane_b32 s10, v254, 10
	v_readlane_b32 s11, v254, 11
	v_sub_u32_e32 v3, v3, v4
	v_mul_hi_u32 v209, v6, s1
	v_readlane_b32 s14, v254, 14
	v_readlane_b32 s15, v254, 15
	v_lshlrev_b32_e32 v150, 3, v5
	v_cmp_gt_u32_e64 s[8:9], 12, v5
	v_cmp_gt_u32_e64 s[10:11], 24, v5
	v_lshlrev_b32_e32 v4, 3, v3
	v_mov_b32_e32 v5, v151
	v_mul_u32_u24_e32 v7, 56, v209
	v_sub_u32_e32 v8, v6, v7
	v_lshl_add_u64 v[158:159], v[4:5], 2, s[28:29]
	v_cmp_gt_u32_e64 s[12:13], 12, v3
	v_cmp_gt_u32_e64 s[14:15], 24, v3
	v_mul_u32_u24_e32 v5, 0x390, v208
	v_lshlrev_b32_e32 v3, 4, v3
	v_add3_u32 v210, 0, v5, v3
	v_mul_u32_u24_e32 v3, 0x390, v209
	v_lshlrev_b32_e32 v5, 4, v8
	v_add3_u32 v211, 0, v3, v5
	v_or_b32_e32 v3, 0x800, v0
	v_mul_hi_u32 v212, v3, s1
	v_mul_u32_u24_e32 v5, 56, v212
	v_sub_u32_e32 v3, v3, v5
	v_or_b32_e32 v5, 0xa00, v0
	v_lshlrev_b32_e32 v6, 3, v8
	v_mov_b32_e32 v7, v151
	v_mul_hi_u32 v213, v5, s1
	v_readlane_b32 s16, v254, 16
	v_readlane_b32 s17, v254, 17
	v_readlane_b32 s18, v254, 18
	v_readlane_b32 s19, v254, 19
	v_lshl_add_u64 v[160:161], v[6:7], 2, s[28:29]
	v_mul_u32_u24_e32 v7, 56, v213
	v_cmp_gt_u32_e64 s[16:17], 12, v8
	v_cmp_gt_u32_e64 s[18:19], 24, v8
	v_lshlrev_b32_e32 v8, 3, v3
	v_sub_u32_e32 v5, v5, v7
	v_cmp_gt_u32_e64 s[20:21], 12, v3
	v_cmp_gt_u32_e64 s[22:23], 24, v3
	v_mul_u32_u24_e32 v7, 0x390, v212
	v_lshlrev_b32_e32 v3, 4, v3
	v_lshlrev_b32_e32 v10, 3, v5
	v_add3_u32 v214, 0, v7, v3
	v_cmp_gt_u32_e64 s[24:25], 12, v5
	v_cmp_gt_u32_e64 s[26:27], 24, v5
	v_mul_u32_u24_e32 v3, 0x390, v213
	v_lshlrev_b32_e32 v5, 4, v5
	v_add3_u32 v215, 0, v3, v5
	v_or_b32_e32 v3, 0xc00, v0
	v_mul_hi_u32 v216, v3, s1
	v_mul_u32_u24_e32 v5, 56, v216
	v_sub_u32_e32 v3, v3, v5
	v_mov_b32_e32 v9, v151
	v_mov_b32_e32 v11, v151
	v_lshlrev_b32_e32 v12, 3, v3
	v_mov_b32_e32 v13, v151
	v_lshl_add_u64 v[156:157], v[150:151], 2, s[28:29]
	v_lshl_add_u64 v[162:163], v[8:9], 2, s[28:29]
	v_lshl_add_u64 v[164:165], v[10:11], 2, s[28:29]
	v_lshl_add_u64 v[166:167], v[12:13], 2, s[28:29]
	v_cmp_gt_u32_e64 s[28:29], 12, v3
	v_cmp_gt_u32_e64 s[30:31], 24, v3
	v_mul_u32_u24_e32 v5, 0x390, v216
	v_lshlrev_b32_e32 v3, 4, v3
	v_add3_u32 v217, 0, v5, v3
	v_lshlrev_b32_e32 v3, 1, v0
	s_lshr_b32 s0, s0, 1
	v_and_b32_e32 v1, 15, v0
	v_and_b32_e32 v3, 24, v3
	v_and_b32_e32 v5, 3, v0
	s_and_b32 s0, s0, 0x7fffffe0
	v_or3_b32 v218, v3, v5, s0
	v_or_b32_e32 v219, s0, v14
	v_mul_u32_u24_e32 v3, 0x390, v1
	v_and_b32_e32 v5, 48, v0
	v_readlane_b32 s0, v254, 0
	v_add3_u32 v220, v3, v5, 0
	s_movk_i32 s3, 0x380
	s_movk_i32 s42, 0x5a00
	v_lshlrev_b32_e32 v150, 1, v150
	s_movk_i32 s43, 0x3000
	s_movk_i32 s44, 0x4010
	v_lshlrev_b32_e32 v168, 1, v2
	s_mov_b32 s45, 0xffff0000
	s_movk_i32 s46, 0x7fff
	v_lshlrev_b32_e32 v170, 1, v6
	v_lshlrev_b32_e32 v172, 1, v4
	v_lshlrev_b32_e32 v174, 1, v10
	v_lshlrev_b32_e32 v176, 1, v8
	v_lshlrev_b32_e32 v178, 1, v12
	s_mov_b32 s47, 0xc1a00000
	s_mov_b32 s48, 0x800000
	s_mov_b32 s49, 0x3f317217
	s_mov_b32 s50, 0x7f800000
	v_mov_b32_e32 v221, 0x41b17218
	s_mov_b32 s51, s0
	v_readlane_b32 s1, v254, 1
	s_branch .LBB0_285

.LBB0_287:
	s_lshl_b32 s33, s72, 6
	v_add_u32_e32 v203, s33, v204
	v_min_i32_e32 v203, 0x400f, v203
	v_mul_u32_u24_e32 v202, s42, v203
	v_add3_u32 v202, v202, v168, s43
	global_load_dwordx4 v[224:227], v202, s[34:35]
	v_add_u32_e32 v203, s33, v204
	v_min_i32_e32 v203, 0x400f, v203
	v_max_i32_e32 v203, 1, v203
	v_add_u32_e32 v203, -1, v203
	v_mul_u32_u24_e32 v202, s42, v203
	v_add3_u32 v202, v202, v168, s43
	global_load_dwordx4 v[228:231], v202, s[34:35]
	v_add_u32_e32 v203, s33, v205
	v_min_i32_e32 v203, 0x400f, v203
	v_mul_u32_u24_e32 v202, s42, v203
	v_add3_u32 v202, v202, v150, s43
	global_load_dwordx4 v[232:235], v202, s[34:35]
	v_add_u32_e32 v203, s33, v205
	v_min_i32_e32 v203, 0x400f, v203
	v_max_i32_e32 v203, 1, v203
	v_add_u32_e32 v203, -1, v203
	v_mul_u32_u24_e32 v202, s42, v203
	v_add3_u32 v202, v202, v150, s43
	global_load_dwordx4 v[236:239], v202, s[34:35]
	v_add_u32_e32 v203, s33, v208
	v_min_i32_e32 v203, 0x400f, v203
	v_mul_u32_u24_e32 v202, s42, v203
	v_add3_u32 v202, v202, v172, s43
	global_load_dwordx4 v[240:243], v202, s[34:35]
	v_add_u32_e32 v203, s33, v208
	v_min_i32_e32 v203, 0x400f, v203
	v_max_i32_e32 v203, 1, v203
	v_add_u32_e32 v203, -1, v203
	v_mul_u32_u24_e32 v202, s42, v203
	v_add3_u32 v202, v202, v172, s43
	global_load_dwordx4 v[244:247], v202, s[34:35]
	v_add_u32_e32 v203, s33, v209
	v_min_i32_e32 v203, 0x400f, v203
	v_mul_u32_u24_e32 v202, s42, v203
	v_add3_u32 v202, v202, v170, s43
	global_load_dwordx4 v[248:251], v202, s[34:35]
	v_or_b32_e32 v171, s33, v205
	v_min_i32_e32 v132, 0x400f, v171
	v_add_u32_e32 v130, -1, v132
	v_cmp_lt_i32_e32 vcc, 0, v171
	s_waitcnt vmcnt(7)
	s_barrier
	v_cndmask_b32_e32 v134, 0, v130, vcc
	v_mov_b64_e32 v[130:131], s[34:35]
	v_mad_i64_i32 v[132:133], s[0:1], v132, s42, v[130:131]
	v_lshl_add_u64 v[132:133], v[132:133], 0, v[150:151]
	v_add_co_u32_e32 v132, vcc, s43, v132
	v_mad_i64_i32 v[130:131], s[0:1], v134, s42, v[130:131]
	s_nop 0
	v_addc_co_u32_e32 v133, vcc, 0, v133, vcc
	v_lshl_add_u64 v[130:131], v[130:131], 0, v[150:151]
	v_add_co_u32_e32 v130, vcc, 0x3000, v130
	s_nop 1
	v_addc_co_u32_e32 v131, vcc, 0, v131, vcc
	s_waitcnt vmcnt(3)
	v_mov_b32_e32 v138, v232
	v_mov_b32_e32 v139, v233
	v_mov_b32_e32 v140, v234
	v_mov_b32_e32 v141, v235
	s_nop 0
	v_mov_b32_e32 v134, v236
	v_mov_b32_e32 v135, v237
	v_mov_b32_e32 v136, v238
	v_mov_b32_e32 v137, v239
	v_add_u32_e32 v203, s33, v209
	v_min_i32_e32 v203, 0x400f, v203
	v_max_i32_e32 v203, 1, v203
	v_add_u32_e32 v203, -1, v203
	v_mul_u32_u24_e32 v202, s42, v203
	v_add3_u32 v202, v202, v170, s43
	global_load_dwordx4 v[232:235], v202, s[34:35]
	v_add_u32_e32 v203, s33, v212
	v_min_i32_e32 v203, 0x400f, v203
	v_mul_u32_u24_e32 v202, s42, v203
	v_add3_u32 v202, v202, v176, s43
	global_load_dwordx4 v[236:239], v202, s[34:35]
	v_or_b32_e32 v131, s33, v204
	v_mov_b32_e32 v130, 0
	v_cmp_gt_i32_e32 vcc, s44, v131
	v_mov_b32_e32 v142, 0
	v_mov_b32_e32 v143, 0
	v_mov_b32_e32 v144, 0
	v_mov_b32_e32 v145, 0
	s_and_saveexec_b64 s[0:1], vcc
	s_cbranch_execz .LBB0_289
	v_max_i32_e32 v132, 1, v131
	v_add_u32_e32 v142, -1, v132
	v_mov_b64_e32 v[132:133], s[34:35]
	v_mad_u64_u32 v[142:143], s[74:75], v142, s42, v[132:133]
	v_mov_b32_e32 v169, v151
	v_lshl_add_u64 v[142:143], v[142:143], 0, v[168:169]
	v_add_co_u32_e32 v142, vcc, 0x3000, v142
	v_mad_i64_i32 v[132:133], s[74:75], v131, s42, v[132:133]
	s_nop 0
	v_addc_co_u32_e32 v143, vcc, 0, v143, vcc
	v_lshl_add_u64 v[132:133], v[132:133], 0, v[168:169]
	s_waitcnt vmcnt(7)
	v_mov_b32_e32 v186, v228
	v_mov_b32_e32 v187, v229
	v_mov_b32_e32 v188, v230
	v_mov_b32_e32 v189, v231
	v_add_co_u32_e32 v132, vcc, 0x3000, v132
	s_waitcnt lgkmcnt(0)
	v_lshlrev_b32_e32 v169, 16, v186
	v_addc_co_u32_e32 v133, vcc, 0, v133, vcc
	s_nop 0
	v_mov_b32_e32 v146, v224
	v_mov_b32_e32 v147, v225
	v_mov_b32_e32 v148, v226
	v_mov_b32_e32 v149, v227
	v_add_u32_e32 v202, s94, v154
	ds_read_b128 v[142:145], v202 offset:16
	ds_read_b128 v[190:193], v202
	v_and_b32_e32 v173, 0xffff0000, v186
	v_lshlrev_b32_e32 v175, 16, v187
	v_and_b32_e32 v177, 0xffff0000, v187
	v_cmp_ne_u32_e32 vcc, 0, v131
	v_lshlrev_b32_e32 v179, 16, v188
	v_lshlrev_b32_e32 v186, 16, v189
	v_cndmask_b32_e32 v199, 0, v175, vcc
	v_cndmask_b32_e32 v198, 0, v169, vcc
	v_cndmask_b32_e32 v187, 0, v186, vcc
	v_cndmask_b32_e32 v186, 0, v179, vcc
	s_waitcnt lgkmcnt(0)
	v_lshlrev_b32_e32 v194, 16, v146
	v_and_b32_e32 v196, 0xffff0000, v146
	v_lshlrev_b32_e32 v195, 16, v147
	v_and_b32_e32 v197, 0xffff0000, v147
	v_lshlrev_b32_e32 v146, 16, v148
	v_and_b32_e32 v132, 0xffff0000, v148
	v_lshlrev_b32_e32 v147, 16, v149
	v_and_b32_e32 v133, 0xffff0000, v149
	v_and_b32_e32 v148, 0xffff0000, v188
	v_and_b32_e32 v149, 0xffff0000, v189
	v_cndmask_b32_e32 v189, 0, v177, vcc
	v_cndmask_b32_e32 v188, 0, v173, vcc
	v_pk_add_f32 v[198:199], v[198:199], v[194:195] neg_lo:[0,1] neg_hi:[0,1]
	s_waitcnt lgkmcnt(0)
	v_mov_b32_e32 v200, v190
	v_mov_b32_e32 v201, v192
	v_pk_add_f32 v[188:189], v[188:189], v[196:197] neg_lo:[0,1] neg_hi:[0,1]
	v_mov_b32_e32 v192, v191
	v_pk_fma_f32 v[194:195], v[200:201], v[198:199], v[194:195]
	v_pk_fma_f32 v[188:189], v[192:193], v[188:189], v[196:197]
	v_add_f32_e32 v131, v194, v194
	v_add_f32_e32 v173, v189, v189
	v_cndmask_b32_e64 v131, -v194, v131, s[4:5]
	v_cndmask_b32_e64 v173, -v189, v173, s[4:5]
	v_mul_f32_e32 v131, 0x3fb8aa3b, v131
	v_mul_f32_e32 v173, 0x3fb8aa3b, v173
	v_exp_f32_e32 v131, v131
	v_exp_f32_e32 v173, v173
	v_cndmask_b32_e32 v149, 0, v149, vcc
	v_cndmask_b32_e32 v148, 0, v148, vcc
	v_add_f32_e32 v131, 1.0, v131
	v_add_f32_e32 v173, 1.0, v173
	v_rcp_f32_e32 v190, v131
	v_add_f32_e32 v131, v188, v188
	v_rcp_f32_e32 v193, v173
	v_cndmask_b32_e64 v131, -v188, v131, s[4:5]
	v_mul_f32_e32 v131, 0x3fb8aa3b, v131
	v_exp_f32_e32 v131, v131
	v_cndmask_b32_e64 v175, v193, v189, s[6:7]
	v_mov_b32_e32 v189, v144
	v_pk_add_f32 v[148:149], v[148:149], v[132:133] neg_lo:[0,1] neg_hi:[0,1]
	v_mov_b32_e32 v144, v143
	v_pk_fma_f32 v[132:133], v[144:145], v[148:149], v[132:133]
	v_add_f32_e32 v131, 1.0, v131
	v_add_f32_e32 v143, v132, v132
	v_cndmask_b32_e64 v143, -v132, v143, s[4:5]
	v_rcp_f32_e32 v192, v131
	v_mul_f32_e32 v143, 0x3fb8aa3b, v143
	v_exp_f32_e32 v143, v143
	v_pk_add_f32 v[186:187], v[186:187], v[146:147] neg_lo:[0,1] neg_hi:[0,1]
	v_cndmask_b32_e64 v173, v192, v188, s[6:7]
	v_mov_b32_e32 v188, v142
	v_pk_fma_f32 v[146:147], v[188:189], v[186:187], v[146:147]
	v_add_f32_e32 v143, 1.0, v143
	v_add_f32_e32 v142, v146, v146
	v_rcp_f32_e32 v144, v143
	v_add_f32_e32 v143, v147, v147
	v_cndmask_b32_e64 v142, -v146, v142, s[4:5]
	v_cndmask_b32_e64 v143, -v147, v143, s[4:5]
	v_mul_f32_e32 v142, 0x3fb8aa3b, v142
	v_mul_f32_e32 v143, 0x3fb8aa3b, v143
	v_exp_f32_e32 v142, v142
	v_exp_f32_e32 v143, v143
	v_add_f32_e32 v131, v195, v195
	v_cndmask_b32_e64 v131, -v195, v131, s[4:5]
	v_add_f32_e32 v142, 1.0, v142
	v_add_f32_e32 v143, 1.0, v143
	v_rcp_f32_e32 v142, v142
	v_rcp_f32_e32 v143, v143
	v_mul_f32_e32 v131, 0x3fb8aa3b, v131
	v_exp_f32_e32 v131, v131
	v_cndmask_b32_e64 v132, v144, v132, s[6:7]
	v_pk_fma_f32 v[148:149], v[142:143], 2.0, 1.0 op_sel_hi:[1,0,0] neg_lo:[1,0,0] neg_hi:[1,0,0]
	v_cndmask_b32_e64 v142, v142, v146, s[6:7]
	v_cndmask_b32_e64 v146, v142, v148, s[4:5]
	v_add_f32_e32 v142, v133, v133
	v_cndmask_b32_e64 v142, -v133, v142, s[4:5]
	v_mul_f32_e32 v142, 0x3fb8aa3b, v142
	v_exp_f32_e32 v142, v142
	v_add_f32_e32 v131, 1.0, v131
	v_rcp_f32_e32 v191, v131
	v_cndmask_b32_e64 v143, v143, v147, s[6:7]
	v_add_f32_e32 v142, 1.0, v142
	v_rcp_f32_e32 v145, v142
	v_cndmask_b32_e64 v147, v143, v149, s[4:5]
	v_pk_fma_f32 v[196:197], v[190:191], 2.0, 1.0 op_sel_hi:[1,0,0] neg_lo:[1,0,0] neg_hi:[1,0,0]
	v_cndmask_b32_e64 v131, v191, v195, s[6:7]
	v_pk_fma_f32 v[142:143], v[144:145], 2.0, 1.0 op_sel_hi:[1,0,0] neg_lo:[1,0,0] neg_hi:[1,0,0]
	v_cndmask_b32_e64 v133, v145, v133, s[6:7]
	v_cndmask_b32_e64 v169, v190, v194, s[6:7]
	v_cndmask_b32_e64 v133, v133, v143, s[4:5]
	v_cndmask_b32_e64 v132, v132, v142, s[4:5]
	v_cndmask_b32_e64 v169, v169, v196, s[4:5]
	v_cndmask_b32_e64 v131, v131, v197, s[4:5]
	v_pk_fma_f32 v[190:191], v[192:193], 2.0, 1.0 op_sel_hi:[1,0,0] neg_lo:[1,0,0] neg_hi:[1,0,0]
	v_bfe_u32 v144, v132, 16, 1
	v_bfe_u32 v145, v133, 16, 1
	v_cndmask_b32_e64 v175, v175, v191, s[4:5]
	v_cndmask_b32_e64 v173, v173, v190, s[4:5]
	v_add3_u32 v133, v133, v145, s46
	v_add3_u32 v132, v132, v144, s46
	v_bfe_u32 v144, v147, 16, 1
	v_bfe_u32 v145, v146, 16, 1
	v_bfe_u32 v148, v131, 16, 1
	v_bfe_u32 v149, v169, 16, 1
	v_bfe_u32 v142, v173, 16, 1
	v_bfe_u32 v143, v175, 16, 1
	v_add3_u32 v149, v169, v149, s46
	v_add3_u32 v131, v131, v148, s46
	v_add3_u32 v145, v146, v145, s46
	v_add3_u32 v144, v147, v144, s46
	v_add3_u32 v143, v175, v143, s46
	v_add3_u32 v142, v173, v142, s46
	v_lshrrev_b32_e32 v146, 16, v144
	v_lshrrev_b32_e32 v144, 16, v145
	v_lshrrev_b32_e32 v131, 16, v131
	v_lshrrev_b32_e32 v145, 16, v149
	v_and_or_b32 v142, v142, s45, v145
	v_and_or_b32 v143, v143, s45, v131
	v_and_or_b32 v144, v132, s45, v144
	v_and_or_b32 v145, v133, s45, v146
.LBB0_289:
	s_or_b64 exec, exec, s[0:1]
	v_add_u32_e32 v203, s33, v212
	v_min_i32_e32 v203, 0x400f, v203
	v_max_i32_e32 v203, 1, v203
	v_add_u32_e32 v203, -1, v203
	v_mul_u32_u24_e32 v202, s42, v203
	v_add3_u32 v202, v202, v176, s43
	global_load_dwordx4 v[224:227], v202, s[34:35]
	v_add_u32_e32 v203, s33, v213
	v_min_i32_e32 v203, 0x400f, v203
	v_mul_u32_u24_e32 v202, s42, v203
	v_add3_u32 v202, v202, v174, s43
	global_load_dwordx4 v[228:231], v202, s[34:35]
	v_cmp_gt_i32_e32 vcc, s44, v171
	v_mov_b32_e32 v131, 0
	v_mov_b32_e32 v132, 0
	v_mov_b32_e32 v133, 0
	ds_write_b128 v206, v[142:145]
	s_and_saveexec_b64 s[0:1], vcc
	s_cbranch_execz .LBB0_291
	v_add_u32_e32 v202, s94, v156
	ds_read_b128 v[130:133], v202 offset:16
	ds_read_b128 v[142:145], v202
	s_waitcnt lgkmcnt(0)
	v_lshlrev_b32_e32 v146, 16, v138
	v_and_b32_e32 v148, 0xffff0000, v138
	v_lshlrev_b32_e32 v147, 16, v139
	v_and_b32_e32 v149, 0xffff0000, v139
	v_lshlrev_b32_e32 v186, 16, v140
	v_and_b32_e32 v138, 0xffff0000, v140
	v_lshlrev_b32_e32 v187, 16, v141
	v_and_b32_e32 v139, 0xffff0000, v141
	s_waitcnt lgkmcnt(0)
	v_and_b32_e32 v140, 0xffff0000, v134
	v_and_b32_e32 v141, 0xffff0000, v135
	v_cmp_ne_u32_e32 vcc, 0, v171
	v_lshlrev_b32_e32 v169, 16, v134
	v_lshlrev_b32_e32 v173, 16, v135
	v_cndmask_b32_e32 v141, 0, v141, vcc
	v_cndmask_b32_e32 v140, 0, v140, vcc
	v_pk_add_f32 v[140:141], v[140:141], v[148:149] neg_lo:[0,1] neg_hi:[0,1]
	v_cndmask_b32_e32 v189, 0, v173, vcc
	v_cndmask_b32_e32 v188, 0, v169, vcc
	v_pk_add_f32 v[188:189], v[188:189], v[146:147] neg_lo:[0,1] neg_hi:[0,1]
	v_and_b32_e32 v134, 0xffff0000, v136
	v_and_b32_e32 v135, 0xffff0000, v137
	v_cndmask_b32_e32 v135, 0, v135, vcc
	v_cndmask_b32_e32 v134, 0, v134, vcc
	v_pk_add_f32 v[134:135], v[134:135], v[138:139] neg_lo:[0,1] neg_hi:[0,1]
	v_lshlrev_b32_e32 v175, 16, v136
	v_lshlrev_b32_e32 v136, 16, v137
	v_cndmask_b32_e32 v137, 0, v136, vcc
	v_cndmask_b32_e32 v136, 0, v175, vcc
	v_pk_add_f32 v[136:137], v[136:137], v[186:187] neg_lo:[0,1] neg_hi:[0,1]
	s_waitcnt lgkmcnt(0)
	v_mov_b32_e32 v191, v144
	v_mov_b32_e32 v144, v143
	v_pk_fma_f32 v[140:141], v[140:141], v[144:145], v[148:149]
	v_mov_b32_e32 v190, v142
	v_add_f32_e32 v143, v140, v140
	v_cndmask_b32_e64 v143, -v140, v143, s[8:9]
	v_mul_f32_e32 v143, 0x3fb8aa3b, v143
	v_exp_f32_e32 v143, v143
	v_pk_fma_f32 v[146:147], v[188:189], v[190:191], v[146:147]
	v_add_f32_e32 v143, 1.0, v143
	v_add_f32_e32 v142, v146, v146
	v_rcp_f32_e32 v144, v143
	v_add_f32_e32 v143, v147, v147
	v_cndmask_b32_e64 v142, -v146, v142, s[8:9]
	v_cndmask_b32_e64 v143, -v147, v143, s[8:9]
	v_mul_f32_e32 v142, 0x3fb8aa3b, v142
	v_mul_f32_e32 v143, 0x3fb8aa3b, v143
	v_exp_f32_e32 v142, v142
	v_exp_f32_e32 v143, v143
	v_cndmask_b32_e64 v140, v144, v140, s[10:11]
	v_add_f32_e32 v142, 1.0, v142
	v_add_f32_e32 v143, 1.0, v143
	v_rcp_f32_e32 v142, v142
	v_rcp_f32_e32 v143, v143
	s_nop 0
	v_pk_fma_f32 v[148:149], v[142:143], 2.0, 1.0 op_sel_hi:[1,0,0] neg_lo:[1,0,0] neg_hi:[1,0,0]
	v_cndmask_b32_e64 v142, v142, v146, s[10:11]
	v_cndmask_b32_e64 v146, v142, v148, s[8:9]
	v_add_f32_e32 v142, v141, v141
	v_cndmask_b32_e64 v142, -v141, v142, s[8:9]
	v_mul_f32_e32 v142, 0x3fb8aa3b, v142
	v_exp_f32_e32 v142, v142
	v_cndmask_b32_e64 v143, v143, v147, s[10:11]
	v_cndmask_b32_e64 v147, v143, v149, s[8:9]
	v_add_f32_e32 v142, 1.0, v142
	v_rcp_f32_e32 v145, v142
	s_nop 0
	v_pk_fma_f32 v[142:143], v[144:145], 2.0, 1.0 op_sel_hi:[1,0,0] neg_lo:[1,0,0] neg_hi:[1,0,0]
	v_cndmask_b32_e64 v141, v145, v141, s[10:11]
	v_cndmask_b32_e64 v143, v141, v143, s[8:9]
	v_mov_b32_e32 v141, v132
	v_mov_b32_e32 v132, v131
	v_pk_fma_f32 v[132:133], v[134:135], v[132:133], v[138:139]
	v_cndmask_b32_e64 v142, v140, v142, s[8:9]
	v_add_f32_e32 v131, v132, v132
	v_cndmask_b32_e64 v131, -v132, v131, s[8:9]
	v_mul_f32_e32 v131, 0x3fb8aa3b, v131
	v_exp_f32_e32 v131, v131
	v_mov_b32_e32 v140, v130
	v_pk_fma_f32 v[136:137], v[136:137], v[140:141], v[186:187]
	v_add_f32_e32 v131, 1.0, v131
	v_add_f32_e32 v130, v136, v136
	v_rcp_f32_e32 v134, v131
	v_add_f32_e32 v131, v137, v137
	v_cndmask_b32_e64 v130, -v136, v130, s[8:9]
	v_cndmask_b32_e64 v131, -v137, v131, s[8:9]
	v_mul_f32_e32 v130, 0x3fb8aa3b, v130
	v_mul_f32_e32 v131, 0x3fb8aa3b, v131
	v_exp_f32_e32 v130, v130
	v_exp_f32_e32 v131, v131
	v_cndmask_b32_e64 v132, v134, v132, s[10:11]
	v_add_f32_e32 v130, 1.0, v130
	v_add_f32_e32 v131, 1.0, v131
	v_rcp_f32_e32 v130, v130
	v_rcp_f32_e32 v131, v131
	s_nop 0
	v_pk_fma_f32 v[138:139], v[130:131], 2.0, 1.0 op_sel_hi:[1,0,0] neg_lo:[1,0,0] neg_hi:[1,0,0]
	v_cndmask_b32_e64 v130, v130, v136, s[10:11]
	v_cndmask_b32_e64 v136, v130, v138, s[8:9]
	v_add_f32_e32 v130, v133, v133
	v_cndmask_b32_e64 v130, -v133, v130, s[8:9]
	v_mul_f32_e32 v130, 0x3fb8aa3b, v130
	v_exp_f32_e32 v130, v130
	v_cndmask_b32_e64 v131, v131, v137, s[10:11]
	v_cndmask_b32_e64 v137, v131, v139, s[8:9]
	v_bfe_u32 v138, v147, 16, 1
	v_add_f32_e32 v130, 1.0, v130
	v_rcp_f32_e32 v135, v130
	v_bfe_u32 v139, v146, 16, 1
	v_add3_u32 v139, v146, v139, s46
	v_add3_u32 v138, v147, v138, s46
	v_pk_fma_f32 v[130:131], v[134:135], 2.0, 1.0 op_sel_hi:[1,0,0] neg_lo:[1,0,0] neg_hi:[1,0,0]
	v_cndmask_b32_e64 v133, v135, v133, s[10:11]
	v_cndmask_b32_e64 v131, v133, v131, s[8:9]
	v_cndmask_b32_e64 v130, v132, v130, s[8:9]
	v_bfe_u32 v132, v142, 16, 1
	v_bfe_u32 v133, v143, 16, 1
	v_bfe_u32 v134, v130, 16, 1
	v_bfe_u32 v135, v131, 16, 1
	v_add3_u32 v135, v131, v135, s46
	v_add3_u32 v134, v130, v134, s46
	v_add3_u32 v131, v143, v133, s46
	v_add3_u32 v130, v142, v132, s46
	v_bfe_u32 v132, v137, 16, 1
	v_bfe_u32 v133, v136, 16, 1
	v_add3_u32 v133, v136, v133, s46
	v_add3_u32 v132, v137, v132, s46
	v_lshrrev_b32_e32 v136, 16, v132
	v_lshrrev_b32_e32 v132, 16, v133
	v_lshrrev_b32_e32 v133, 16, v138
	v_lshrrev_b32_e32 v137, 16, v139
	v_and_or_b32 v130, v130, s45, v137
	v_and_or_b32 v131, v131, s45, v133
	v_and_or_b32 v132, v134, s45, v132
	v_and_or_b32 v133, v135, s45, v136
.LBB0_291:
	s_or_b64 exec, exec, s[0:1]
	v_add_u32_e32 v146, s33, v209
	s_waitcnt lgkmcnt(0)
	v_min_i32_e32 v136, 0x400f, v146
	v_add_u32_e32 v134, -1, v136
	v_cmp_lt_i32_e32 vcc, 0, v146
	v_mov_b32_e32 v171, v151
	v_mov_b32_e32 v142, 0
	v_cndmask_b32_e32 v138, 0, v134, vcc
	v_mov_b64_e32 v[134:135], s[34:35]
	v_mad_i64_i32 v[136:137], s[0:1], v136, s42, v[134:135]
	v_lshl_add_u64 v[136:137], v[136:137], 0, v[170:171]
	v_add_co_u32_e32 v136, vcc, s43, v136
	v_mad_i64_i32 v[134:135], s[0:1], v138, s42, v[134:135]
	s_nop 0
	v_addc_co_u32_e32 v137, vcc, 0, v137, vcc
	v_lshl_add_u64 v[134:135], v[134:135], 0, v[170:171]
	v_add_co_u32_e32 v134, vcc, 0x3000, v134
	v_mov_b32_e32 v143, 0
	s_nop 0
	v_addc_co_u32_e32 v135, vcc, 0, v135, vcc
	s_waitcnt vmcnt(3)
	v_mov_b32_e32 v138, v248
	v_mov_b32_e32 v139, v249
	v_mov_b32_e32 v140, v250
	v_mov_b32_e32 v141, v251
	s_nop 0
	s_nop 0
	v_mov_b32_e32 v134, v232
	v_mov_b32_e32 v135, v233
	v_mov_b32_e32 v136, v234
	v_mov_b32_e32 v137, v235
	v_add_u32_e32 v203, s33, v213
	v_min_i32_e32 v203, 0x400f, v203
	v_max_i32_e32 v203, 1, v203
	v_add_u32_e32 v203, -1, v203
	v_mul_u32_u24_e32 v202, s42, v203
	v_add3_u32 v202, v202, v174, s43
	global_load_dwordx4 v[248:251], v202, s[34:35]
	v_add_u32_e32 v203, s33, v216
	v_min_i32_e32 v203, 0x400f, v203
	v_mul_u32_u24_e32 v202, s42, v203
	v_add3_u32 v202, v202, v178, s43
	global_load_dwordx4 v[232:235], v202, s[34:35]
	ds_write_b128 v207, v[130:133]
	v_or_b32_e32 v131, s33, v208
	v_mov_b32_e32 v130, 0
	v_cmp_gt_i32_e32 vcc, s44, v131
	v_mov_b32_e32 v144, 0
	v_mov_b32_e32 v145, 0
	s_and_saveexec_b64 s[0:1], vcc
	s_cbranch_execz .LBB0_293
	v_max_i32_e32 v132, 1, v131
	v_add_u32_e32 v142, -1, v132
	v_mov_b64_e32 v[132:133], s[34:35]
	v_mad_u64_u32 v[142:143], s[74:75], v142, s42, v[132:133]
	v_mov_b32_e32 v173, v151
	v_lshl_add_u64 v[148:149], v[142:143], 0, v[172:173]
	v_add_co_u32_e32 v148, vcc, 0x3000, v148
	v_mad_i64_i32 v[132:133], s[74:75], v131, s42, v[132:133]
	s_nop 0
	v_addc_co_u32_e32 v149, vcc, 0, v149, vcc
	v_lshl_add_u64 v[132:133], v[132:133], 0, v[172:173]
	v_add_co_u32_e32 v132, vcc, 0x3000, v132
	v_add_u32_e32 v202, s94, v158
	ds_read_b128 v[142:145], v202 offset:16
	ds_read_b128 v[186:189], v202
	v_addc_co_u32_e32 v133, vcc, 0, v133, vcc
	s_waitcnt vmcnt(7)
	v_mov_b32_e32 v190, v244
	v_mov_b32_e32 v191, v245
	v_mov_b32_e32 v192, v246
	v_mov_b32_e32 v193, v247
	s_nop 0
	v_mov_b32_e32 v194, v240
	v_mov_b32_e32 v195, v241
	v_mov_b32_e32 v196, v242
	v_mov_b32_e32 v197, v243
	s_waitcnt lgkmcnt(0)
	v_mov_b32_e32 v148, v142
	s_waitcnt lgkmcnt(0)
	v_mov_b32_e32 v132, v186
	v_mov_b32_e32 v133, v188
	v_mov_b32_e32 v188, v187
	v_mov_b32_e32 v149, v144
	v_mov_b32_e32 v144, v143
	s_waitcnt lgkmcnt(0)
	v_lshlrev_b32_e32 v142, 16, v190
	v_and_b32_e32 v186, 0xffff0000, v190
	v_lshlrev_b32_e32 v143, 16, v191
	v_and_b32_e32 v187, 0xffff0000, v191
	s_waitcnt lgkmcnt(0)
	v_lshlrev_b32_e32 v198, 16, v194
	v_and_b32_e32 v194, 0xffff0000, v194
	v_lshlrev_b32_e32 v199, 16, v195
	v_and_b32_e32 v195, 0xffff0000, v195
	v_pk_add_f32 v[142:143], v[142:143], v[198:199] neg_lo:[0,1] neg_hi:[0,1]
	v_pk_add_f32 v[186:187], v[186:187], v[194:195] neg_lo:[0,1] neg_hi:[0,1]
	v_pk_fma_f32 v[132:133], v[132:133], v[142:143], v[198:199]
	v_pk_fma_f32 v[142:143], v[188:189], v[186:187], v[194:195]
	v_add_f32_e32 v131, v132, v132
	v_add_f32_e32 v147, v142, v142
	v_add_f32_e32 v169, v133, v133
	v_add_f32_e32 v171, v143, v143
	v_cndmask_b32_e64 v131, -v132, v131, s[12:13]
	v_cndmask_b32_e64 v147, -v142, v147, s[12:13]
	v_cndmask_b32_e64 v169, -v133, v169, s[12:13]
	v_cndmask_b32_e64 v171, -v143, v171, s[12:13]
	v_mul_f32_e32 v131, 0x3fb8aa3b, v131
	v_mul_f32_e32 v147, 0x3fb8aa3b, v147
	v_mul_f32_e32 v169, 0x3fb8aa3b, v169
	v_mul_f32_e32 v171, 0x3fb8aa3b, v171
	v_exp_f32_e32 v131, v131
	v_exp_f32_e32 v147, v147
	v_exp_f32_e32 v169, v169
	v_exp_f32_e32 v171, v171
	v_add_f32_e32 v131, 1.0, v131
	v_add_f32_e32 v147, 1.0, v147
	v_add_f32_e32 v169, 1.0, v169
	v_add_f32_e32 v171, 1.0, v171
	v_rcp_f32_e32 v186, v131
	v_rcp_f32_e32 v187, v169
	v_rcp_f32_e32 v188, v147
	v_rcp_f32_e32 v189, v171
	v_lshlrev_b32_e32 v190, 16, v192
	v_lshlrev_b32_e32 v191, 16, v193
	v_lshlrev_b32_e32 v200, 16, v196
	v_lshlrev_b32_e32 v201, 16, v197
	v_and_b32_e32 v192, 0xffff0000, v192
	v_and_b32_e32 v193, 0xffff0000, v193
	v_and_b32_e32 v196, 0xffff0000, v196
	v_and_b32_e32 v197, 0xffff0000, v197
	v_pk_add_f32 v[190:191], v[190:191], v[200:201] neg_lo:[0,1] neg_hi:[0,1]
	v_pk_add_f32 v[192:193], v[192:193], v[196:197] neg_lo:[0,1] neg_hi:[0,1]
	v_pk_fma_f32 v[148:149], v[148:149], v[190:191], v[200:201]
	v_pk_fma_f32 v[144:145], v[144:145], v[192:193], v[196:197]
	v_add_f32_e32 v173, v148, v148
	v_add_f32_e32 v177, v149, v149
	v_cndmask_b32_e64 v131, v187, v133, s[14:15]
	v_cndmask_b32_e64 v147, v186, v132, s[14:15]
	v_pk_fma_f32 v[132:133], v[188:189], 2.0, 1.0 op_sel_hi:[1,0,0] neg_lo:[1,0,0] neg_hi:[1,0,0]
	v_cndmask_b32_e64 v142, v188, v142, s[14:15]
	v_add_f32_e32 v175, v144, v144
	v_cndmask_b32_e64 v173, -v148, v173, s[12:13]
	v_cndmask_b32_e64 v177, -v149, v177, s[12:13]
	v_cndmask_b32_e64 v171, v142, v132, s[12:13]
	v_add_f32_e32 v132, v145, v145
	v_cndmask_b32_e64 v175, -v144, v175, s[12:13]
	v_mul_f32_e32 v173, 0x3fb8aa3b, v173
	v_mul_f32_e32 v177, 0x3fb8aa3b, v177
	v_cndmask_b32_e64 v132, -v145, v132, s[12:13]
	v_mul_f32_e32 v175, 0x3fb8aa3b, v175
	v_exp_f32_e32 v173, v173
	v_exp_f32_e32 v177, v177
	v_cndmask_b32_e64 v143, v189, v143, s[14:15]
	v_mul_f32_e32 v132, 0x3fb8aa3b, v132
	v_exp_f32_e32 v175, v175
	v_cndmask_b32_e64 v169, v143, v133, s[12:13]
	v_exp_f32_e32 v133, v132
	v_add_f32_e32 v173, 1.0, v173
	v_add_f32_e32 v177, 1.0, v177
	v_add_f32_e32 v175, 1.0, v175
	v_rcp_f32_e32 v190, v173
	v_rcp_f32_e32 v191, v177
	v_add_f32_e32 v133, 1.0, v133
	v_rcp_f32_e32 v132, v175
	v_rcp_f32_e32 v133, v133
	v_pk_fma_f32 v[142:143], v[190:191], 2.0, 1.0 op_sel_hi:[1,0,0] neg_lo:[1,0,0] neg_hi:[1,0,0]
	v_cndmask_b32_e64 v149, v191, v149, s[14:15]
	v_cndmask_b32_e64 v148, v190, v148, s[14:15]
	v_cndmask_b32_e64 v148, v148, v142, s[12:13]
	v_cndmask_b32_e64 v149, v149, v143, s[12:13]
	v_pk_fma_f32 v[142:143], v[132:133], 2.0, 1.0 op_sel_hi:[1,0,0] neg_lo:[1,0,0] neg_hi:[1,0,0]
	v_cndmask_b32_e64 v132, v132, v144, s[14:15]
	v_cndmask_b32_e64 v133, v133, v145, s[14:15]
	v_pk_fma_f32 v[192:193], v[186:187], 2.0, 1.0 op_sel_hi:[1,0,0] neg_lo:[1,0,0] neg_hi:[1,0,0]
	v_cndmask_b32_e64 v133, v133, v143, s[12:13]
	v_cndmask_b32_e64 v132, v132, v142, s[12:13]
	v_cndmask_b32_e64 v147, v147, v192, s[12:13]
	v_cndmask_b32_e64 v131, v131, v193, s[12:13]
	v_bfe_u32 v142, v132, 16, 1
	v_bfe_u32 v143, v133, 16, 1
	v_bfe_u32 v144, v171, 16, 1
	v_bfe_u32 v145, v169, 16, 1
	v_add3_u32 v133, v133, v143, s46
	v_add3_u32 v132, v132, v142, s46
	v_add3_u32 v143, v169, v145, s46
	v_add3_u32 v142, v171, v144, s46
	v_bfe_u32 v144, v131, 16, 1
	v_bfe_u32 v145, v147, 16, 1
	v_bfe_u32 v169, v149, 16, 1
	v_bfe_u32 v171, v148, 16, 1
	v_add3_u32 v148, v148, v171, s46
	v_add3_u32 v149, v149, v169, s46
	v_add3_u32 v145, v147, v145, s46
	v_add3_u32 v131, v131, v144, s46
	v_lshrrev_b32_e32 v131, 16, v131
	v_lshrrev_b32_e32 v147, 16, v145
	v_lshrrev_b32_e32 v145, 16, v149
	v_lshrrev_b32_e32 v144, 16, v148
	v_and_or_b32 v144, v132, s45, v144
	v_and_or_b32 v145, v133, s45, v145
	v_and_or_b32 v142, v142, s45, v147
	v_and_or_b32 v143, v143, s45, v131
.LBB0_293:
	s_or_b64 exec, exec, s[0:1]
	v_add_u32_e32 v203, s33, v216
	v_min_i32_e32 v203, 0x400f, v203
	v_max_i32_e32 v203, 1, v203
	v_add_u32_e32 v203, -1, v203
	v_mul_u32_u24_e32 v202, s42, v203
	v_add3_u32 v202, v202, v178, s43
	global_load_dwordx4 v[240:243], v202, s[34:35]
	v_cmp_gt_i32_e32 vcc, s44, v146
	v_mov_b32_e32 v131, 0
	v_mov_b32_e32 v132, 0
	v_mov_b32_e32 v133, 0
	ds_write_b128 v210, v[142:145]
	s_and_saveexec_b64 s[0:1], vcc
	s_cbranch_execz .LBB0_295
	v_add_u32_e32 v202, s94, v160
	ds_read_b128 v[130:133], v202 offset:16
	ds_read_b128 v[142:145], v202
	s_waitcnt lgkmcnt(0)
	v_lshlrev_b32_e32 v148, 16, v138
	v_and_b32_e32 v186, 0xffff0000, v138
	v_lshlrev_b32_e32 v149, 16, v139
	v_and_b32_e32 v187, 0xffff0000, v139
	v_lshlrev_b32_e32 v188, 16, v140
	v_and_b32_e32 v138, 0xffff0000, v140
	v_lshlrev_b32_e32 v189, 16, v141
	v_and_b32_e32 v139, 0xffff0000, v141
	s_waitcnt lgkmcnt(0)
	v_and_b32_e32 v140, 0xffff0000, v134
	v_and_b32_e32 v141, 0xffff0000, v135
	v_cmp_ne_u32_e32 vcc, 0, v146
	v_lshlrev_b32_e32 v169, 16, v134
	v_lshlrev_b32_e32 v147, 16, v135
	v_cndmask_b32_e32 v141, 0, v141, vcc
	v_cndmask_b32_e32 v140, 0, v140, vcc
	v_pk_add_f32 v[140:141], v[140:141], v[186:187] neg_lo:[0,1] neg_hi:[0,1]
	v_cndmask_b32_e32 v147, 0, v147, vcc
	v_cndmask_b32_e32 v146, 0, v169, vcc
	v_pk_add_f32 v[146:147], v[146:147], v[148:149] neg_lo:[0,1] neg_hi:[0,1]
	v_and_b32_e32 v134, 0xffff0000, v136
	v_and_b32_e32 v135, 0xffff0000, v137
	v_cndmask_b32_e32 v135, 0, v135, vcc
	v_cndmask_b32_e32 v134, 0, v134, vcc
	v_pk_add_f32 v[134:135], v[134:135], v[138:139] neg_lo:[0,1] neg_hi:[0,1]
	v_lshlrev_b32_e32 v171, 16, v136
	v_lshlrev_b32_e32 v136, 16, v137
	v_cndmask_b32_e32 v137, 0, v136, vcc
	v_cndmask_b32_e32 v136, 0, v171, vcc
	v_pk_add_f32 v[136:137], v[136:137], v[188:189] neg_lo:[0,1] neg_hi:[0,1]
	s_waitcnt lgkmcnt(0)
	v_mov_b32_e32 v191, v144
	v_mov_b32_e32 v144, v143
	v_pk_fma_f32 v[140:141], v[140:141], v[144:145], v[186:187]
	v_mov_b32_e32 v190, v142
	v_add_f32_e32 v143, v140, v140
	v_cndmask_b32_e64 v143, -v140, v143, s[16:17]
	v_mul_f32_e32 v143, 0x3fb8aa3b, v143
	v_exp_f32_e32 v143, v143
	v_pk_fma_f32 v[146:147], v[146:147], v[190:191], v[148:149]
	v_add_f32_e32 v143, 1.0, v143
	v_add_f32_e32 v142, v146, v146
	v_rcp_f32_e32 v144, v143
	v_add_f32_e32 v143, v147, v147
	v_cndmask_b32_e64 v142, -v146, v142, s[16:17]
	v_cndmask_b32_e64 v143, -v147, v143, s[16:17]
	v_mul_f32_e32 v142, 0x3fb8aa3b, v142
	v_mul_f32_e32 v143, 0x3fb8aa3b, v143
	v_exp_f32_e32 v142, v142
	v_exp_f32_e32 v143, v143
	v_cndmask_b32_e64 v140, v144, v140, s[18:19]
	v_add_f32_e32 v142, 1.0, v142
	v_add_f32_e32 v143, 1.0, v143
	v_rcp_f32_e32 v142, v142
	v_rcp_f32_e32 v143, v143
	s_nop 0
	v_pk_fma_f32 v[148:149], v[142:143], 2.0, 1.0 op_sel_hi:[1,0,0] neg_lo:[1,0,0] neg_hi:[1,0,0]
	v_cndmask_b32_e64 v142, v142, v146, s[18:19]
	v_cndmask_b32_e64 v146, v142, v148, s[16:17]
	v_add_f32_e32 v142, v141, v141
	v_cndmask_b32_e64 v142, -v141, v142, s[16:17]
	v_mul_f32_e32 v142, 0x3fb8aa3b, v142
	v_exp_f32_e32 v142, v142
	v_cndmask_b32_e64 v143, v143, v147, s[18:19]
	v_cndmask_b32_e64 v147, v143, v149, s[16:17]
	v_add_f32_e32 v142, 1.0, v142
	v_rcp_f32_e32 v145, v142
	s_nop 0
	v_pk_fma_f32 v[142:143], v[144:145], 2.0, 1.0 op_sel_hi:[1,0,0] neg_lo:[1,0,0] neg_hi:[1,0,0]
	v_cndmask_b32_e64 v141, v145, v141, s[18:19]
	v_cndmask_b32_e64 v143, v141, v143, s[16:17]
	v_mov_b32_e32 v141, v132
	v_mov_b32_e32 v132, v131
	v_pk_fma_f32 v[132:133], v[134:135], v[132:133], v[138:139]
	v_cndmask_b32_e64 v142, v140, v142, s[16:17]
	v_add_f32_e32 v131, v132, v132
	v_cndmask_b32_e64 v131, -v132, v131, s[16:17]
	v_mul_f32_e32 v131, 0x3fb8aa3b, v131
	v_exp_f32_e32 v131, v131
	v_mov_b32_e32 v140, v130
	v_pk_fma_f32 v[136:137], v[136:137], v[140:141], v[188:189]
	v_add_f32_e32 v131, 1.0, v131
	v_add_f32_e32 v130, v136, v136
	v_rcp_f32_e32 v134, v131
	v_add_f32_e32 v131, v137, v137
	v_cndmask_b32_e64 v130, -v136, v130, s[16:17]
	v_cndmask_b32_e64 v131, -v137, v131, s[16:17]
	v_mul_f32_e32 v130, 0x3fb8aa3b, v130
	v_mul_f32_e32 v131, 0x3fb8aa3b, v131
	v_exp_f32_e32 v130, v130
	v_exp_f32_e32 v131, v131
	v_cndmask_b32_e64 v132, v134, v132, s[18:19]
	v_add_f32_e32 v130, 1.0, v130
	v_add_f32_e32 v131, 1.0, v131
	v_rcp_f32_e32 v130, v130
	v_rcp_f32_e32 v131, v131
	s_nop 0
	v_pk_fma_f32 v[138:139], v[130:131], 2.0, 1.0 op_sel_hi:[1,0,0] neg_lo:[1,0,0] neg_hi:[1,0,0]
	v_cndmask_b32_e64 v130, v130, v136, s[18:19]
	v_cndmask_b32_e64 v136, v130, v138, s[16:17]
	v_add_f32_e32 v130, v133, v133
	v_cndmask_b32_e64 v130, -v133, v130, s[16:17]
	v_mul_f32_e32 v130, 0x3fb8aa3b, v130
	v_exp_f32_e32 v130, v130
	v_cndmask_b32_e64 v131, v131, v137, s[18:19]
	v_cndmask_b32_e64 v137, v131, v139, s[16:17]
	v_bfe_u32 v138, v147, 16, 1
	v_add_f32_e32 v130, 1.0, v130
	v_rcp_f32_e32 v135, v130
	v_bfe_u32 v139, v146, 16, 1
	v_add3_u32 v139, v146, v139, s46
	v_add3_u32 v138, v147, v138, s46
	v_pk_fma_f32 v[130:131], v[134:135], 2.0, 1.0 op_sel_hi:[1,0,0] neg_lo:[1,0,0] neg_hi:[1,0,0]
	v_cndmask_b32_e64 v133, v135, v133, s[18:19]
	v_cndmask_b32_e64 v131, v133, v131, s[16:17]
	v_cndmask_b32_e64 v130, v132, v130, s[16:17]
	v_bfe_u32 v132, v142, 16, 1
	v_bfe_u32 v133, v143, 16, 1
	v_bfe_u32 v134, v130, 16, 1
	v_bfe_u32 v135, v131, 16, 1
	v_add3_u32 v135, v131, v135, s46
	v_add3_u32 v134, v130, v134, s46
	v_add3_u32 v131, v143, v133, s46
	v_add3_u32 v130, v142, v132, s46
	v_bfe_u32 v132, v137, 16, 1
	v_bfe_u32 v133, v136, 16, 1
	v_add3_u32 v133, v136, v133, s46
	v_add3_u32 v132, v137, v132, s46
	v_lshrrev_b32_e32 v136, 16, v132
	v_lshrrev_b32_e32 v132, 16, v133
	v_lshrrev_b32_e32 v133, 16, v138
	v_lshrrev_b32_e32 v137, 16, v139
	v_and_or_b32 v130, v130, s45, v137
	v_and_or_b32 v131, v131, s45, v133
	v_and_or_b32 v132, v134, s45, v132
	v_and_or_b32 v133, v135, s45, v136
.LBB0_295:
	s_or_b64 exec, exec, s[0:1]
	v_add_u32_e32 v146, s33, v213
	s_waitcnt lgkmcnt(0)
	v_min_i32_e32 v136, 0x400f, v146
	v_add_u32_e32 v134, -1, v136
	v_cmp_lt_i32_e32 vcc, 0, v146
	v_mov_b32_e32 v175, v151
	v_mov_b32_e32 v142, 0
	v_cndmask_b32_e32 v138, 0, v134, vcc
	v_mov_b64_e32 v[134:135], s[34:35]
	v_mad_i64_i32 v[136:137], s[0:1], v136, s42, v[134:135]
	v_lshl_add_u64 v[136:137], v[136:137], 0, v[174:175]
	v_add_co_u32_e32 v136, vcc, s43, v136
	v_mad_i64_i32 v[134:135], s[0:1], v138, s42, v[134:135]
	s_nop 0
	v_addc_co_u32_e32 v137, vcc, 0, v137, vcc
	v_lshl_add_u64 v[134:135], v[134:135], 0, v[174:175]
	v_add_co_u32_e32 v134, vcc, 0x3000, v134
	v_mov_b32_e32 v143, 0
	s_nop 0
	v_addc_co_u32_e32 v135, vcc, 0, v135, vcc
	s_waitcnt vmcnt(2)
	v_mov_b32_e32 v138, v228
	v_mov_b32_e32 v139, v229
	v_mov_b32_e32 v140, v230
	v_mov_b32_e32 v141, v231
	s_nop 0
	s_nop 0
	v_mov_b32_e32 v134, v248
	v_mov_b32_e32 v135, v249
	v_mov_b32_e32 v136, v250
	v_mov_b32_e32 v137, v251
	ds_write_b128 v211, v[130:133]
	v_or_b32_e32 v131, s33, v212
	v_mov_b32_e32 v130, 0
	v_cmp_gt_i32_e32 vcc, s44, v131
	v_mov_b32_e32 v144, 0
	v_mov_b32_e32 v145, 0
	s_and_saveexec_b64 s[0:1], vcc
	s_cbranch_execz .LBB0_297
	v_max_i32_e32 v132, 1, v131
	v_add_u32_e32 v142, -1, v132
	v_mov_b64_e32 v[132:133], s[34:35]
	v_mad_u64_u32 v[142:143], s[74:75], v142, s42, v[132:133]
	v_mov_b32_e32 v177, v151
	v_lshl_add_u64 v[148:149], v[142:143], 0, v[176:177]
	v_add_co_u32_e32 v148, vcc, 0x3000, v148
	v_mad_i64_i32 v[132:133], s[74:75], v131, s42, v[132:133]
	s_nop 0
	v_addc_co_u32_e32 v149, vcc, 0, v149, vcc
	v_lshl_add_u64 v[132:133], v[132:133], 0, v[176:177]
	v_add_co_u32_e32 v132, vcc, 0x3000, v132
	v_add_u32_e32 v202, s94, v162
	ds_read_b128 v[142:145], v202 offset:16
	ds_read_b128 v[186:189], v202
	v_addc_co_u32_e32 v133, vcc, 0, v133, vcc
	s_waitcnt vmcnt(7)
	v_mov_b32_e32 v190, v224
	v_mov_b32_e32 v191, v225
	v_mov_b32_e32 v192, v226
	v_mov_b32_e32 v193, v227
	s_nop 0
	v_mov_b32_e32 v194, v236
	v_mov_b32_e32 v195, v237
	v_mov_b32_e32 v196, v238
	v_mov_b32_e32 v197, v239
	s_waitcnt lgkmcnt(0)
	v_mov_b32_e32 v148, v142
	s_waitcnt lgkmcnt(0)
	v_mov_b32_e32 v132, v186
	v_mov_b32_e32 v133, v188
	v_mov_b32_e32 v188, v187
	v_mov_b32_e32 v149, v144
	v_mov_b32_e32 v144, v143
	s_waitcnt lgkmcnt(0)
	v_lshlrev_b32_e32 v142, 16, v190
	v_and_b32_e32 v186, 0xffff0000, v190
	v_lshlrev_b32_e32 v143, 16, v191
	v_and_b32_e32 v187, 0xffff0000, v191
	s_waitcnt lgkmcnt(0)
	v_lshlrev_b32_e32 v198, 16, v194
	v_and_b32_e32 v194, 0xffff0000, v194
	v_lshlrev_b32_e32 v199, 16, v195
	v_and_b32_e32 v195, 0xffff0000, v195
	v_pk_add_f32 v[142:143], v[142:143], v[198:199] neg_lo:[0,1] neg_hi:[0,1]
	v_pk_add_f32 v[186:187], v[186:187], v[194:195] neg_lo:[0,1] neg_hi:[0,1]
	v_pk_fma_f32 v[132:133], v[132:133], v[142:143], v[198:199]
	v_pk_fma_f32 v[142:143], v[188:189], v[186:187], v[194:195]
	v_add_f32_e32 v131, v132, v132
	v_add_f32_e32 v147, v142, v142
	v_add_f32_e32 v169, v133, v133
	v_add_f32_e32 v171, v143, v143
	v_cndmask_b32_e64 v131, -v132, v131, s[20:21]
	v_cndmask_b32_e64 v147, -v142, v147, s[20:21]
	v_cndmask_b32_e64 v169, -v133, v169, s[20:21]
	v_cndmask_b32_e64 v171, -v143, v171, s[20:21]
	v_mul_f32_e32 v131, 0x3fb8aa3b, v131
	v_mul_f32_e32 v147, 0x3fb8aa3b, v147
	v_mul_f32_e32 v169, 0x3fb8aa3b, v169
	v_mul_f32_e32 v171, 0x3fb8aa3b, v171
	v_exp_f32_e32 v131, v131
	v_exp_f32_e32 v147, v147
	v_exp_f32_e32 v169, v169
	v_exp_f32_e32 v171, v171
	v_add_f32_e32 v131, 1.0, v131
	v_add_f32_e32 v147, 1.0, v147
	v_add_f32_e32 v169, 1.0, v169
	v_add_f32_e32 v171, 1.0, v171
	v_rcp_f32_e32 v186, v131
	v_rcp_f32_e32 v187, v169
	v_rcp_f32_e32 v188, v147
	v_rcp_f32_e32 v189, v171
	v_lshlrev_b32_e32 v190, 16, v192
	v_lshlrev_b32_e32 v191, 16, v193
	v_lshlrev_b32_e32 v200, 16, v196
	v_lshlrev_b32_e32 v201, 16, v197
	v_and_b32_e32 v192, 0xffff0000, v192
	v_and_b32_e32 v193, 0xffff0000, v193
	v_and_b32_e32 v196, 0xffff0000, v196
	v_and_b32_e32 v197, 0xffff0000, v197
	v_pk_add_f32 v[190:191], v[190:191], v[200:201] neg_lo:[0,1] neg_hi:[0,1]
	v_pk_add_f32 v[192:193], v[192:193], v[196:197] neg_lo:[0,1] neg_hi:[0,1]
	v_pk_fma_f32 v[148:149], v[148:149], v[190:191], v[200:201]
	v_pk_fma_f32 v[144:145], v[144:145], v[192:193], v[196:197]
	v_add_f32_e32 v173, v148, v148
	v_add_f32_e32 v177, v149, v149
	v_cndmask_b32_e64 v131, v187, v133, s[22:23]
	v_cndmask_b32_e64 v147, v186, v132, s[22:23]
	v_pk_fma_f32 v[132:133], v[188:189], 2.0, 1.0 op_sel_hi:[1,0,0] neg_lo:[1,0,0] neg_hi:[1,0,0]
	v_cndmask_b32_e64 v142, v188, v142, s[22:23]
	v_add_f32_e32 v175, v144, v144
	v_cndmask_b32_e64 v173, -v148, v173, s[20:21]
	v_cndmask_b32_e64 v177, -v149, v177, s[20:21]
	v_cndmask_b32_e64 v171, v142, v132, s[20:21]
	v_add_f32_e32 v132, v145, v145
	v_cndmask_b32_e64 v175, -v144, v175, s[20:21]
	v_mul_f32_e32 v173, 0x3fb8aa3b, v173
	v_mul_f32_e32 v177, 0x3fb8aa3b, v177
	v_cndmask_b32_e64 v132, -v145, v132, s[20:21]
	v_mul_f32_e32 v175, 0x3fb8aa3b, v175
	v_exp_f32_e32 v173, v173
	v_exp_f32_e32 v177, v177
	v_cndmask_b32_e64 v143, v189, v143, s[22:23]
	v_mul_f32_e32 v132, 0x3fb8aa3b, v132
	v_exp_f32_e32 v175, v175
	v_cndmask_b32_e64 v169, v143, v133, s[20:21]
	v_exp_f32_e32 v133, v132
	v_add_f32_e32 v173, 1.0, v173
	v_add_f32_e32 v177, 1.0, v177
	v_add_f32_e32 v175, 1.0, v175
	v_rcp_f32_e32 v190, v173
	v_rcp_f32_e32 v191, v177
	v_add_f32_e32 v133, 1.0, v133
	v_rcp_f32_e32 v132, v175
	v_rcp_f32_e32 v133, v133
	v_pk_fma_f32 v[142:143], v[190:191], 2.0, 1.0 op_sel_hi:[1,0,0] neg_lo:[1,0,0] neg_hi:[1,0,0]
	v_cndmask_b32_e64 v149, v191, v149, s[22:23]
	v_cndmask_b32_e64 v148, v190, v148, s[22:23]
	v_cndmask_b32_e64 v148, v148, v142, s[20:21]
	v_cndmask_b32_e64 v149, v149, v143, s[20:21]
	v_pk_fma_f32 v[142:143], v[132:133], 2.0, 1.0 op_sel_hi:[1,0,0] neg_lo:[1,0,0] neg_hi:[1,0,0]
	v_cndmask_b32_e64 v132, v132, v144, s[22:23]
	v_cndmask_b32_e64 v133, v133, v145, s[22:23]
	v_pk_fma_f32 v[192:193], v[186:187], 2.0, 1.0 op_sel_hi:[1,0,0] neg_lo:[1,0,0] neg_hi:[1,0,0]
	v_cndmask_b32_e64 v133, v133, v143, s[20:21]
	v_cndmask_b32_e64 v132, v132, v142, s[20:21]
	v_cndmask_b32_e64 v147, v147, v192, s[20:21]
	v_cndmask_b32_e64 v131, v131, v193, s[20:21]
	v_bfe_u32 v142, v132, 16, 1
	v_bfe_u32 v143, v133, 16, 1
	v_bfe_u32 v144, v171, 16, 1
	v_bfe_u32 v145, v169, 16, 1
	v_add3_u32 v133, v133, v143, s46
	v_add3_u32 v132, v132, v142, s46
	v_add3_u32 v143, v169, v145, s46
	v_add3_u32 v142, v171, v144, s46
	v_bfe_u32 v144, v131, 16, 1
	v_bfe_u32 v145, v147, 16, 1
	v_bfe_u32 v169, v149, 16, 1
	v_bfe_u32 v171, v148, 16, 1
	v_add3_u32 v148, v148, v171, s46
	v_add3_u32 v149, v149, v169, s46
	v_add3_u32 v145, v147, v145, s46
	v_add3_u32 v131, v131, v144, s46
	v_lshrrev_b32_e32 v131, 16, v131
	v_lshrrev_b32_e32 v147, 16, v145
	v_lshrrev_b32_e32 v145, 16, v149
	v_lshrrev_b32_e32 v144, 16, v148
	v_and_or_b32 v144, v132, s45, v144
	v_and_or_b32 v145, v133, s45, v145
	v_and_or_b32 v142, v142, s45, v147
	v_and_or_b32 v143, v143, s45, v131
.LBB0_297:
	s_or_b64 exec, exec, s[0:1]
	v_cmp_gt_i32_e32 vcc, s44, v146
	v_mov_b32_e32 v131, 0
	v_mov_b32_e32 v132, 0
	v_mov_b32_e32 v133, 0
	ds_write_b128 v214, v[142:145]
	s_and_saveexec_b64 s[0:1], vcc
	s_cbranch_execz .LBB0_299
	v_add_u32_e32 v202, s94, v164
	ds_read_b128 v[130:133], v202 offset:16
	ds_read_b128 v[142:145], v202
	s_waitcnt lgkmcnt(0)
	v_lshlrev_b32_e32 v148, 16, v138
	v_and_b32_e32 v186, 0xffff0000, v138
	v_lshlrev_b32_e32 v149, 16, v139
	v_and_b32_e32 v187, 0xffff0000, v139
	v_lshlrev_b32_e32 v188, 16, v140
	v_and_b32_e32 v138, 0xffff0000, v140
	v_lshlrev_b32_e32 v189, 16, v141
	v_and_b32_e32 v139, 0xffff0000, v141
	s_waitcnt lgkmcnt(0)
	v_and_b32_e32 v140, 0xffff0000, v134
	v_and_b32_e32 v141, 0xffff0000, v135
	v_cmp_ne_u32_e32 vcc, 0, v146
	v_lshlrev_b32_e32 v169, 16, v134
	v_lshlrev_b32_e32 v147, 16, v135
	v_cndmask_b32_e32 v141, 0, v141, vcc
	v_cndmask_b32_e32 v140, 0, v140, vcc
	v_pk_add_f32 v[140:141], v[140:141], v[186:187] neg_lo:[0,1] neg_hi:[0,1]
	v_cndmask_b32_e32 v147, 0, v147, vcc
	v_cndmask_b32_e32 v146, 0, v169, vcc
	v_pk_add_f32 v[146:147], v[146:147], v[148:149] neg_lo:[0,1] neg_hi:[0,1]
	v_and_b32_e32 v134, 0xffff0000, v136
	v_and_b32_e32 v135, 0xffff0000, v137
	v_cndmask_b32_e32 v135, 0, v135, vcc
	v_cndmask_b32_e32 v134, 0, v134, vcc
	v_pk_add_f32 v[134:135], v[134:135], v[138:139] neg_lo:[0,1] neg_hi:[0,1]
	v_lshlrev_b32_e32 v171, 16, v136
	v_lshlrev_b32_e32 v136, 16, v137
	v_cndmask_b32_e32 v137, 0, v136, vcc
	v_cndmask_b32_e32 v136, 0, v171, vcc
	v_pk_add_f32 v[136:137], v[136:137], v[188:189] neg_lo:[0,1] neg_hi:[0,1]
	s_waitcnt lgkmcnt(0)
	v_mov_b32_e32 v191, v144
	v_mov_b32_e32 v144, v143
	v_pk_fma_f32 v[140:141], v[140:141], v[144:145], v[186:187]
	v_mov_b32_e32 v190, v142
	v_add_f32_e32 v143, v140, v140
	v_cndmask_b32_e64 v143, -v140, v143, s[24:25]
	v_mul_f32_e32 v143, 0x3fb8aa3b, v143
	v_exp_f32_e32 v143, v143
	v_pk_fma_f32 v[146:147], v[146:147], v[190:191], v[148:149]
	v_add_f32_e32 v143, 1.0, v143
	v_add_f32_e32 v142, v146, v146
	v_rcp_f32_e32 v144, v143
	v_add_f32_e32 v143, v147, v147
	v_cndmask_b32_e64 v142, -v146, v142, s[24:25]
	v_cndmask_b32_e64 v143, -v147, v143, s[24:25]
	v_mul_f32_e32 v142, 0x3fb8aa3b, v142
	v_mul_f32_e32 v143, 0x3fb8aa3b, v143
	v_exp_f32_e32 v142, v142
	v_exp_f32_e32 v143, v143
	v_cndmask_b32_e64 v140, v144, v140, s[26:27]
	v_add_f32_e32 v142, 1.0, v142
	v_add_f32_e32 v143, 1.0, v143
	v_rcp_f32_e32 v142, v142
	v_rcp_f32_e32 v143, v143
	s_nop 0
	v_pk_fma_f32 v[148:149], v[142:143], 2.0, 1.0 op_sel_hi:[1,0,0] neg_lo:[1,0,0] neg_hi:[1,0,0]
	v_cndmask_b32_e64 v142, v142, v146, s[26:27]
	v_cndmask_b32_e64 v146, v142, v148, s[24:25]
	v_add_f32_e32 v142, v141, v141
	v_cndmask_b32_e64 v142, -v141, v142, s[24:25]
	v_mul_f32_e32 v142, 0x3fb8aa3b, v142
	v_exp_f32_e32 v142, v142
	v_cndmask_b32_e64 v143, v143, v147, s[26:27]
	v_cndmask_b32_e64 v147, v143, v149, s[24:25]
	v_add_f32_e32 v142, 1.0, v142
	v_rcp_f32_e32 v145, v142
	s_nop 0
	v_pk_fma_f32 v[142:143], v[144:145], 2.0, 1.0 op_sel_hi:[1,0,0] neg_lo:[1,0,0] neg_hi:[1,0,0]
	v_cndmask_b32_e64 v141, v145, v141, s[26:27]
	v_cndmask_b32_e64 v143, v141, v143, s[24:25]
	v_mov_b32_e32 v141, v132
	v_mov_b32_e32 v132, v131
	v_pk_fma_f32 v[132:133], v[134:135], v[132:133], v[138:139]
	v_cndmask_b32_e64 v142, v140, v142, s[24:25]
	v_add_f32_e32 v131, v132, v132
	v_cndmask_b32_e64 v131, -v132, v131, s[24:25]
	v_mul_f32_e32 v131, 0x3fb8aa3b, v131
	v_exp_f32_e32 v131, v131
	v_mov_b32_e32 v140, v130
	v_pk_fma_f32 v[136:137], v[136:137], v[140:141], v[188:189]
	v_add_f32_e32 v131, 1.0, v131
	v_add_f32_e32 v130, v136, v136
	v_rcp_f32_e32 v134, v131
	v_add_f32_e32 v131, v137, v137
	v_cndmask_b32_e64 v130, -v136, v130, s[24:25]
	v_cndmask_b32_e64 v131, -v137, v131, s[24:25]
	v_mul_f32_e32 v130, 0x3fb8aa3b, v130
	v_mul_f32_e32 v131, 0x3fb8aa3b, v131
	v_exp_f32_e32 v130, v130
	v_exp_f32_e32 v131, v131
	v_cndmask_b32_e64 v132, v134, v132, s[26:27]
	v_add_f32_e32 v130, 1.0, v130
	v_add_f32_e32 v131, 1.0, v131
	v_rcp_f32_e32 v130, v130
	v_rcp_f32_e32 v131, v131
	s_nop 0
	v_pk_fma_f32 v[138:139], v[130:131], 2.0, 1.0 op_sel_hi:[1,0,0] neg_lo:[1,0,0] neg_hi:[1,0,0]
	v_cndmask_b32_e64 v130, v130, v136, s[26:27]
	v_cndmask_b32_e64 v136, v130, v138, s[24:25]
	v_add_f32_e32 v130, v133, v133
	v_cndmask_b32_e64 v130, -v133, v130, s[24:25]
	v_mul_f32_e32 v130, 0x3fb8aa3b, v130
	v_exp_f32_e32 v130, v130
	v_cndmask_b32_e64 v131, v131, v137, s[26:27]
	v_cndmask_b32_e64 v137, v131, v139, s[24:25]
	v_bfe_u32 v138, v147, 16, 1
	v_add_f32_e32 v130, 1.0, v130
	v_rcp_f32_e32 v135, v130
	v_bfe_u32 v139, v146, 16, 1
	v_add3_u32 v139, v146, v139, s46
	v_add3_u32 v138, v147, v138, s46
	v_pk_fma_f32 v[130:131], v[134:135], 2.0, 1.0 op_sel_hi:[1,0,0] neg_lo:[1,0,0] neg_hi:[1,0,0]
	v_cndmask_b32_e64 v133, v135, v133, s[26:27]
	v_cndmask_b32_e64 v131, v133, v131, s[24:25]
	v_cndmask_b32_e64 v130, v132, v130, s[24:25]
	v_bfe_u32 v132, v142, 16, 1
	v_bfe_u32 v133, v143, 16, 1
	v_bfe_u32 v134, v130, 16, 1
	v_bfe_u32 v135, v131, 16, 1
	v_add3_u32 v135, v131, v135, s46
	v_add3_u32 v134, v130, v134, s46
	v_add3_u32 v131, v143, v133, s46
	v_add3_u32 v130, v142, v132, s46
	v_bfe_u32 v132, v137, 16, 1
	v_bfe_u32 v133, v136, 16, 1
	v_add3_u32 v133, v136, v133, s46
	v_add3_u32 v132, v137, v132, s46
	v_lshrrev_b32_e32 v136, 16, v132
	v_lshrrev_b32_e32 v132, 16, v133
	v_lshrrev_b32_e32 v133, 16, v138
	v_lshrrev_b32_e32 v137, 16, v139
	v_and_or_b32 v130, v130, s45, v137
	v_and_or_b32 v131, v131, s45, v133
	v_and_or_b32 v132, v134, s45, v132
	v_and_or_b32 v133, v135, s45, v136
.LBB0_299:
	s_or_b64 exec, exec, s[0:1]
	s_waitcnt lgkmcnt(0)
	v_add_u32_e32 v138, s33, v216
	ds_write_b128 v215, v[130:133]
	v_cmp_gt_i32_e32 vcc, s44, v138
	v_mov_b32_e32 v130, 0
	v_mov_b32_e32 v131, 0
	v_mov_b32_e32 v132, 0
	v_mov_b32_e32 v133, 0
	s_and_saveexec_b64 s[0:1], vcc
	s_cbranch_execz .LBB0_301
	v_max_i32_e32 v130, 1, v138
	v_add_u32_e32 v132, -1, v130
	v_mov_b64_e32 v[130:131], s[34:35]
	v_mad_u64_u32 v[132:133], s[74:75], v132, s42, v[130:131]
	v_mov_b32_e32 v179, v151
	v_lshl_add_u64 v[132:133], v[132:133], 0, v[178:179]
	v_add_co_u32_e32 v132, vcc, 0x3000, v132
	v_mad_i64_i32 v[130:131], s[74:75], v138, s42, v[130:131]
	s_nop 0
	v_addc_co_u32_e32 v133, vcc, 0, v133, vcc
	v_lshl_add_u64 v[130:131], v[130:131], 0, v[178:179]
	s_waitcnt vmcnt(0)
	v_mov_b32_e32 v140, v240
	v_mov_b32_e32 v141, v241
	v_mov_b32_e32 v142, v242
	v_mov_b32_e32 v143, v243
	v_add_co_u32_e32 v130, vcc, 0x3000, v130
	s_waitcnt lgkmcnt(0)
	v_lshlrev_b32_e32 v169, 16, v141
	v_addc_co_u32_e32 v131, vcc, 0, v131, vcc
	s_nop 0
	v_mov_b32_e32 v144, v232
	v_mov_b32_e32 v145, v233
	v_mov_b32_e32 v146, v234
	v_mov_b32_e32 v147, v235
	s_nop 0
	v_add_u32_e32 v202, s94, v166
	ds_read_b128 v[130:133], v202 offset:16
	ds_read_b128 v[186:189], v202
	v_and_b32_e32 v171, 0xffff0000, v141
	v_and_b32_e32 v141, 0xffff0000, v142
	v_cmp_ne_u32_e32 vcc, 0, v138
	v_and_b32_e32 v139, 0xffff0000, v143
	s_waitcnt lgkmcnt(0)
	v_lshlrev_b32_e32 v136, 16, v146
	v_and_b32_e32 v134, 0xffff0000, v146
	v_lshlrev_b32_e32 v137, 16, v147
	v_and_b32_e32 v135, 0xffff0000, v147
	v_lshlrev_b32_e32 v146, 16, v140
	v_and_b32_e32 v147, 0xffff0000, v140
	v_lshlrev_b32_e32 v140, 16, v142
	v_lshlrev_b32_e32 v142, 16, v143
	v_lshlrev_b32_e32 v148, 16, v144
	v_lshlrev_b32_e32 v149, 16, v145
	v_cndmask_b32_e32 v138, 0, v141, vcc
	v_cndmask_b32_e32 v141, 0, v142, vcc
	v_cndmask_b32_e32 v142, 0, v147, vcc
	v_cndmask_b32_e32 v147, 0, v169, vcc
	v_cndmask_b32_e32 v146, 0, v146, vcc
	v_and_b32_e32 v144, 0xffff0000, v144
	v_and_b32_e32 v145, 0xffff0000, v145
	v_cndmask_b32_e32 v143, 0, v171, vcc
	v_pk_add_f32 v[146:147], v[146:147], v[148:149] neg_lo:[0,1] neg_hi:[0,1]
	s_waitcnt lgkmcnt(0)
	v_mov_b32_e32 v190, v186
	v_mov_b32_e32 v191, v188
	v_pk_fma_f32 v[146:147], v[190:191], v[146:147], v[148:149]
	v_pk_add_f32 v[142:143], v[142:143], v[144:145] neg_lo:[0,1] neg_hi:[0,1]
	v_mov_b32_e32 v188, v187
	v_add_f32_e32 v148, v146, v146
	v_pk_fma_f32 v[142:143], v[188:189], v[142:143], v[144:145]
	v_add_f32_e32 v145, v147, v147
	v_cndmask_b32_e64 v148, -v146, v148, s[28:29]
	v_cndmask_b32_e64 v145, -v147, v145, s[28:29]
	v_mul_f32_e32 v148, 0x3fb8aa3b, v148
	v_mul_f32_e32 v145, 0x3fb8aa3b, v145
	v_exp_f32_e32 v148, v148
	v_exp_f32_e32 v145, v145
	v_add_f32_e32 v144, v142, v142
	v_cndmask_b32_e64 v144, -v142, v144, s[28:29]
	v_add_f32_e32 v148, 1.0, v148
	v_add_f32_e32 v145, 1.0, v145
	v_rcp_f32_e32 v148, v148
	v_rcp_f32_e32 v149, v145
	v_mul_f32_e32 v144, 0x3fb8aa3b, v144
	v_exp_f32_e32 v144, v144
	v_cndmask_b32_e64 v146, v148, v146, s[30:31]
	v_pk_fma_f32 v[186:187], v[148:149], 2.0, 1.0 op_sel_hi:[1,0,0] neg_lo:[1,0,0] neg_hi:[1,0,0]
	v_cndmask_b32_e64 v145, v149, v147, s[30:31]
	v_cndmask_b32_e64 v149, v145, v187, s[28:29]
	v_add_f32_e32 v145, v143, v143
	v_cndmask_b32_e64 v145, -v143, v145, s[28:29]
	v_mul_f32_e32 v145, 0x3fb8aa3b, v145
	v_exp_f32_e32 v145, v145
	v_add_f32_e32 v144, 1.0, v144
	v_rcp_f32_e32 v144, v144
	v_cndmask_b32_e32 v139, 0, v139, vcc
	v_add_f32_e32 v145, 1.0, v145
	v_rcp_f32_e32 v145, v145
	v_cndmask_b32_e64 v148, v146, v186, s[28:29]
	v_cndmask_b32_e64 v142, v144, v142, s[30:31]
	v_pk_add_f32 v[138:139], v[138:139], v[134:135] neg_lo:[0,1] neg_hi:[0,1]
	v_pk_fma_f32 v[146:147], v[144:145], 2.0, 1.0 op_sel_hi:[1,0,0] neg_lo:[1,0,0] neg_hi:[1,0,0]
	v_cndmask_b32_e64 v143, v145, v143, s[30:31]
	v_cndmask_b32_e64 v144, v143, v147, s[28:29]
	v_mov_b32_e32 v143, v132
	v_mov_b32_e32 v132, v131
	v_pk_fma_f32 v[132:133], v[132:133], v[138:139], v[134:135]
	v_cndmask_b32_e32 v140, 0, v140, vcc
	v_add_f32_e32 v131, v132, v132
	v_cndmask_b32_e64 v131, -v132, v131, s[28:29]
	v_mul_f32_e32 v131, 0x3fb8aa3b, v131
	v_exp_f32_e32 v131, v131
	v_cndmask_b32_e64 v145, v142, v146, s[28:29]
	v_pk_add_f32 v[140:141], v[140:141], v[136:137] neg_lo:[0,1] neg_hi:[0,1]
	v_mov_b32_e32 v142, v130
	v_pk_fma_f32 v[136:137], v[142:143], v[140:141], v[136:137]
	v_add_f32_e32 v131, 1.0, v131
	v_add_f32_e32 v130, v136, v136
	v_rcp_f32_e32 v134, v131
	v_add_f32_e32 v131, v137, v137
	v_cndmask_b32_e64 v130, -v136, v130, s[28:29]
	v_cndmask_b32_e64 v131, -v137, v131, s[28:29]
	v_mul_f32_e32 v130, 0x3fb8aa3b, v130
	v_mul_f32_e32 v131, 0x3fb8aa3b, v131
	v_exp_f32_e32 v130, v130
	v_exp_f32_e32 v131, v131
	v_cndmask_b32_e64 v132, v134, v132, s[30:31]
	v_add_f32_e32 v130, 1.0, v130
	v_add_f32_e32 v131, 1.0, v131
	v_rcp_f32_e32 v130, v130
	v_rcp_f32_e32 v131, v131
	s_nop 0
	v_pk_fma_f32 v[138:139], v[130:131], 2.0, 1.0 op_sel_hi:[1,0,0] neg_lo:[1,0,0] neg_hi:[1,0,0]
	v_cndmask_b32_e64 v130, v130, v136, s[30:31]
	v_cndmask_b32_e64 v136, v130, v138, s[28:29]
	v_add_f32_e32 v130, v133, v133
	v_cndmask_b32_e64 v130, -v133, v130, s[28:29]
	v_mul_f32_e32 v130, 0x3fb8aa3b, v130
	v_exp_f32_e32 v130, v130
	v_cndmask_b32_e64 v131, v131, v137, s[30:31]
	v_cndmask_b32_e64 v137, v131, v139, s[28:29]
	v_bfe_u32 v138, v149, 16, 1
	v_add_f32_e32 v130, 1.0, v130
	v_rcp_f32_e32 v135, v130
	v_bfe_u32 v139, v148, 16, 1
	v_add3_u32 v139, v148, v139, s46
	v_add3_u32 v138, v149, v138, s46
	v_pk_fma_f32 v[130:131], v[134:135], 2.0, 1.0 op_sel_hi:[1,0,0] neg_lo:[1,0,0] neg_hi:[1,0,0]
	v_cndmask_b32_e64 v133, v135, v133, s[30:31]
	v_cndmask_b32_e64 v131, v133, v131, s[28:29]
	v_cndmask_b32_e64 v130, v132, v130, s[28:29]
	v_bfe_u32 v132, v145, 16, 1
	v_bfe_u32 v133, v144, 16, 1
	v_bfe_u32 v134, v130, 16, 1
	v_bfe_u32 v135, v131, 16, 1
	v_add3_u32 v135, v131, v135, s46
	v_add3_u32 v134, v130, v134, s46
	v_add3_u32 v131, v144, v133, s46
	v_add3_u32 v130, v145, v132, s46
	v_bfe_u32 v132, v137, 16, 1
	v_bfe_u32 v133, v136, 16, 1
	v_add3_u32 v133, v136, v133, s46
	v_add3_u32 v132, v137, v132, s46
	v_lshrrev_b32_e32 v136, 16, v132
	v_lshrrev_b32_e32 v132, 16, v133
	v_lshrrev_b32_e32 v133, 16, v138
	v_lshrrev_b32_e32 v137, 16, v139
	v_and_or_b32 v130, v130, s45, v137
	v_and_or_b32 v131, v131, s45, v133
	v_and_or_b32 v132, v134, s45, v132
	v_and_or_b32 v133, v135, s45, v136
